# attention epilogues: issue the 4 z-gate loads together (MoBA + both NSA unit epilogues), counted vmcnt waits
# speedup vs baseline: 1.0319x; 1.0319x over previous
; __device__ __forceinline__ int fresh_tid(int wv) { return wv * 64 + fresh_lane(); }
; __device__ __forceinline__ unsigned cvtpk(float lo, float hi) { f32x2_t v = {lo, hi}; bf16x2_t b = __builtin_convertvector(v, bf16x2_t); return __builtin_bit_cast(unsigned, b); }
; __device__ __forceinline__ float sigmoidf_(float x) { return __builtin_amdgcn_rcpf(1.f + fexp2(-1.4426950408889634f * x)); }
; __device__ __forceinline__ void attn_epilogue(const f32x16& a0, const f32x16& a1, float scale, const bf16* zrow, bf16* orow, int hi) {
; #pragma unroll
;     for (int db = 0; db < 2; ++db)
; #pragma unroll
;         for (int p = 0; p < 2; ++p) {
;             const f32x16& o = db ? a1 : a0;
;             float x[4], y[4];
; #pragma unroll
;             for (int i = 0; i < 4; ++i) {
;                 auto rr = __builtin_amdgcn_permlane32_swap(__float_as_uint(o[8 * p + i]), __float_as_uint(o[8 * p + 4 + i]), false, false);
;                 x[i] = __uint_as_float(rr[0]); y[i] = __uint_as_float(rr[1]);
;             }
;             const int d = 32 * db + 8 * (2 * p + hi);
;             const v4u zz = *(const v4u*)(zrow + d);
;             f32x4 za, zb; unpack8(zz, za, zb);
;             float v[8];
; #pragma unroll
;             for (int i = 0; i < 4; ++i) { v[i] = x[i] * scale * za[i] * sigmoidf_(za[i]); v[4 + i] = y[i] * scale * zb[i] * sigmoidf_(zb[i]); }
;             *(v4u*)(orow + d) = (v4u){cvtpk(v[0], v[1]), cvtpk(v[2], v[3]), cvtpk(v[4], v[5]), cvtpk(v[6], v[7])};
;         }
; }
; __device__ __forceinline__ void nsa_unit(const int wv, LAS unsigned char* lds, int b, int g, int c, const bf16* Y, const bf16* KCMP, const bf16* VCMP, const float* gates, bf16* OG) {
;     ...
;         const float l = swap_sum(o2[0]); const float s = g2 / l;
; #pragma unroll
;         for (int r = 0; r < 16; ++r) { acc0[r] = accs[r * 512] + s * o0[r]; acc1[r] = accs[(16 + r) * 512] + s * o1[r]; }
;     }
;     const int tid3 = fresh_tid(wv); const int hi3 = (tid3 >> 5) & 1, hh3 = 4 * g + (tid3 >> 7); const size_t row3 = (size_t)b * T + 64 * c + 32 * ((tid3 >> 6) & 1) + (tid3 & 31);
;     attn_epilogue(acc0, acc1, 1.0f, Y + row3 * NSA_LDY + 2048 + hh3 * 64, OG + row3 * D + hh3 * 64, hi3);
.LBB0_839:
	v_mov_b32_e32 v32, v34
	s_nop 1
	v_permlane32_swap_b32_e32 v34, v32
	v_add_f32_e32 v32, v34, v32
	v_div_scale_f32 v33, s[0:1], v32, v32, v184
	v_rcp_f32_e32 v34, v33
	ds_read2st64_b32 v[40:41], v185 offset0:48 offset1:56
	ds_read2st64_b32 v[38:39], v185 offset1:8
	ds_read2st64_b32 v[42:43], v185 offset0:32 offset1:40
	v_fma_f32 v35, -v33, v34, 1.0
	v_fmac_f32_e32 v34, v35, v34
	v_div_scale_f32 v35, vcc, v184, v32, v184
	v_mul_f32_e32 v36, v35, v34
	v_fma_f32 v37, -v33, v36, v35
	v_fmac_f32_e32 v36, v37, v34
	v_fma_f32 v33, -v33, v36, v35
	v_div_fmas_f32 v33, v33, v34, v36
	ds_read2st64_b32 v[34:35], v185 offset0:128 offset1:136
	v_div_fixup_f32 v44, v33, v32, v184
	ds_read2st64_b32 v[36:37], v185 offset0:16 offset1:24
	ds_read2st64_b32 v[32:33], v185 offset0:144 offset1:152
	s_waitcnt lgkmcnt(5)
	v_fma_f32 v40, v6, v44, v40
	s_waitcnt lgkmcnt(2)
	v_fma_f32 v34, v16, v44, v34
	v_fmac_f32_e32 v35, v17, v44
	ds_read2st64_b32 v[16:17], v185 offset0:192 offset1:200
	s_waitcnt lgkmcnt(2)
	v_fma_f32 v36, v2, v44, v36
	v_fmac_f32_e32 v37, v3, v44
	ds_read2st64_b32 v[2:3], v185 offset0:176 offset1:184
	s_waitcnt lgkmcnt(2)
	v_fma_f32 v32, v18, v44, v32
	s_waitcnt lgkmcnt(1)
	v_fma_f32 v16, v24, v44, v16
	v_fmac_f32_e32 v17, v25, v44
	ds_read2st64_b32 v[24:25], v185 offset0:96 offset1:104
	v_fmac_f32_e32 v33, v19, v44
	ds_read2st64_b32 v[18:19], v185 offset0:160 offset1:168
	s_waitcnt lgkmcnt(2)
	v_fma_f32 v2, v22, v44, v2
	v_fmac_f32_e32 v41, v7, v44
	v_fmac_f32_e32 v3, v23, v44
	ds_read2st64_b32 v[22:23], v185 offset0:64 offset1:72
	ds_read2st64_b32 v[6:7], v185 offset0:208 offset1:216
	s_waitcnt lgkmcnt(3)
	v_fma_f32 v24, v12, v44, v24
	v_fmac_f32_e32 v25, v13, v44
	ds_read2st64_b32 v[12:13], v185 offset0:112 offset1:120
	v_fma_f32 v38, v0, v44, v38
	v_fma_f32 v42, v4, v44, v42
	s_waitcnt lgkmcnt(3)
	v_fma_f32 v18, v20, v44, v18
	v_fmac_f32_e32 v43, v5, v44
	v_fmac_f32_e32 v19, v21, v44
	s_waitcnt lgkmcnt(2)
	v_fma_f32 v22, v8, v44, v22
	v_fmac_f32_e32 v23, v9, v44
	ds_read2st64_b32 v[20:21], v185 offset0:80 offset1:88
	s_waitcnt lgkmcnt(2)
	v_fma_f32 v6, v26, v44, v6
	ds_read2st64_b32 v[8:9], v185 offset0:224 offset1:232
	ds_read2st64_b32 v[4:5], v185 offset0:240 offset1:248
	v_mbcnt_lo_u32_b32 v26, -1, 0
	v_mbcnt_hi_u32_b32 v26, -1, v26
	s_waitcnt lgkmcnt(3)
	v_fma_f32 v12, v14, v44, v12
	v_add_u32_e32 v0, s83, v26
	v_ashrrev_i32_e32 v14, 7, v0
	v_lshrrev_b32_e32 v0, 1, v0
	v_fmac_f32_e32 v39, v1, v44
	v_and_b32_e32 v0, 32, v0
	v_and_b32_e32 v1, 31, v26
	v_readlane_b32 s0, v255, 13
	s_waitcnt lgkmcnt(2)
	v_fma_f32 v20, v10, v44, v20
	v_fmac_f32_e32 v21, v11, v44
	v_or3_b32 v0, s0, v0, v1
	v_readlane_b32 s0, v254, 27
	v_readlane_b32 s1, v254, 28
	v_readlane_b32 s4, v255, 14
	v_fmac_f32_e32 v13, v15, v44
	v_mov_b64_e32 v[10:11], s[0:1]
	v_mad_u64_u32 v[10:11], s[0:1], v0, s84, v[10:11]
	v_readlane_b32 s0, v254, 21
	v_mov_b32_e32 v1, s4
	v_lshlrev_b64 v[0:1], 11, v[0:1]
	v_add_lshl_u32 v14, v14, s0, 6
	v_readlane_b32 s0, v254, 25
	v_ashrrev_i32_e32 v15, 31, v14
	v_readlane_b32 s1, v254, 26
	v_mad_i32_i24 v11, s4, v246, v11
	v_lshlrev_b64 v[14:15], 1, v[14:15]
	v_lshl_add_u64 v[0:1], s[0:1], 0, v[0:1]
	v_lshl_add_u64 v[10:11], v[10:11], 0, v[14:15]
	v_lshl_add_u64 v[14:15], v[0:1], 0, v[14:15]
	v_lshrrev_b32_e32 v0, 1, v26
	v_and_b32_e32 v114, 16, v0
	v_lshl_add_u64 v[10:11], v[10:11], 0, v[114:115]
	s_mov_b64 s[0:1], 0x1000
	v_lshl_add_u64 v[0:1], v[10:11], 0, s[0:1]
	s_movk_i32 s0, 0x1000
	v_add_co_u32_e32 v10, vcc, s0, v10
	v_fmac_f32_e32 v7, v27, v44
	s_nop 0
	v_addc_co_u32_e32 v11, vcc, 0, v11, vcc
	s_waitcnt lgkmcnt(1)
	v_fma_f32 v8, v28, v44, v8
	v_fmac_f32_e32 v9, v29, v44
	global_load_dwordx4 v[26:29], v[10:11], off
	global_load_dwordx4 v[82:85], v[0:1], off offset:32
	global_load_dwordx4 v[86:89], v[0:1], off offset:64
	global_load_dwordx4 v[90:93], v[0:1], off offset:96
	v_permlane32_swap_b32_e32 v38, v42
	v_permlane32_swap_b32_e32 v39, v43
	s_waitcnt lgkmcnt(0)
	v_fma_f32 v4, v30, v44, v4
	v_fmac_f32_e32 v5, v31, v44
	v_permlane32_swap_b32_e32 v36, v40
	v_permlane32_swap_b32_e32 v37, v41
	v_permlane32_swap_b32_e32 v22, v24
	v_permlane32_swap_b32_e32 v23, v25
	v_permlane32_swap_b32_e32 v20, v12
	v_permlane32_swap_b32_e32 v21, v13
	v_permlane32_swap_b32_e32 v34, v18
	v_permlane32_swap_b32_e32 v35, v19
	v_permlane32_swap_b32_e32 v32, v2
	v_permlane32_swap_b32_e32 v33, v3
	v_permlane32_swap_b32_e32 v16, v8
	v_permlane32_swap_b32_e32 v17, v9
	v_permlane32_swap_b32_e32 v6, v4
	v_permlane32_swap_b32_e32 v7, v5
	s_add_i32 s19, s19, 1
	s_cmp_eq_u32 s19, 4
	s_waitcnt vmcnt(3)
	v_lshlrev_b32_e32 v10, 16, v26
	v_and_b32_e32 v11, 0xffff0000, v26
	v_mul_f32_e32 v26, 0xbfb8aa3b, v10
	v_pk_mul_f32 v[38:39], v[38:39], v[10:11]
	v_mul_f32_e32 v10, 0xbfb8aa3b, v11
	v_exp_f32_e32 v26, v26
	v_exp_f32_e32 v10, v10
	v_add_f32_e32 v26, 1.0, v26
	v_add_f32_e32 v10, 1.0, v10
	v_rcp_f32_e32 v30, v26
	v_rcp_f32_e32 v31, v10
	s_nop 0
	v_pk_mul_f32 v[10:11], v[38:39], v[30:31]
	v_lshlrev_b32_e32 v30, 16, v28
	v_mul_f32_e32 v26, 0xbfb8aa3b, v30
	v_exp_f32_e32 v26, v26
	v_and_b32_e32 v31, 0xffff0000, v28
	v_pk_mul_f32 v[42:43], v[42:43], v[30:31]
	v_add_f32_e32 v26, 1.0, v26
	v_rcp_f32_e32 v38, v26
	v_mul_f32_e32 v26, 0xbfb8aa3b, v31
	v_exp_f32_e32 v26, v26
	s_nop 0
	v_add_f32_e32 v26, 1.0, v26
	v_rcp_f32_e32 v39, v26
	v_lshlrev_b32_e32 v26, 16, v27
	v_and_b32_e32 v27, 0xffff0000, v27
	v_mul_f32_e32 v28, 0xbfb8aa3b, v26
	v_pk_mul_f32 v[36:37], v[36:37], v[26:27]
	v_mul_f32_e32 v26, 0xbfb8aa3b, v27
	v_exp_f32_e32 v28, v28
	v_exp_f32_e32 v26, v26
	v_pk_mul_f32 v[30:31], v[42:43], v[38:39]
	v_and_b32_e32 v27, 0xffff0000, v29
	v_add_f32_e32 v28, 1.0, v28
	v_add_f32_e32 v26, 1.0, v26
	v_rcp_f32_e32 v38, v28
	v_rcp_f32_e32 v39, v26
	v_lshlrev_b32_e32 v26, 16, v29
	v_mul_f32_e32 v28, 0xbfb8aa3b, v26
	v_exp_f32_e32 v28, v28
	v_pk_mul_f32 v[36:37], v[36:37], v[38:39]
	v_pk_mul_f32 v[38:39], v[40:41], v[26:27]
	v_mul_f32_e32 v26, 0xbfb8aa3b, v27
	v_exp_f32_e32 v26, v26
	v_add_f32_e32 v28, 1.0, v28
	v_rcp_f32_e32 v28, v28
	v_cvt_pk_bf16_f32 v27, v36, v37
	v_add_f32_e32 v26, 1.0, v26
	v_rcp_f32_e32 v29, v26
	v_cvt_pk_bf16_f32 v26, v10, v11
	v_lshl_add_u64 v[10:11], v[14:15], 0, v[114:115]
	v_pk_mul_f32 v[38:39], v[38:39], v[28:29]
	v_cvt_pk_bf16_f32 v28, v30, v31
	v_cvt_pk_bf16_f32 v29, v38, v39
	global_store_dwordx4 v[10:11], v[26:29], off
	s_waitcnt vmcnt(3)
; __device__ __forceinline__ unsigned cvtpk(float lo, float hi) { f32x2_t v = {lo, hi}; bf16x2_t b = __builtin_convertvector(v, bf16x2_t); return __builtin_bit_cast(unsigned, b); }
; __device__ __forceinline__ float sigmoidf_(float x) { return __builtin_amdgcn_rcpf(1.f + fexp2(-1.4426950408889634f * x)); }
; __device__ __forceinline__ void attn_epilogue(const f32x16& a0, const f32x16& a1, float scale, const bf16* zrow, bf16* orow, int hi) {
; #pragma unroll
;     for (int db = 0; db < 2; ++db)
; #pragma unroll
;         for (int p = 0; p < 2; ++p) {
;             const f32x16& o = db ? a1 : a0;
;             float x[4], y[4];
; #pragma unroll
;             for (int i = 0; i < 4; ++i) {
;                 auto rr = __builtin_amdgcn_permlane32_swap(__float_as_uint(o[8 * p + i]), __float_as_uint(o[8 * p + 4 + i]), false, false);
;                 x[i] = __uint_as_float(rr[0]); y[i] = __uint_as_float(rr[1]);
;             }
;             const int d = 32 * db + 8 * (2 * p + hi);
;             const v4u zz = *(const v4u*)(zrow + d);
;             f32x4 za, zb; unpack8(zz, za, zb);
;             float v[8];
; #pragma unroll
;             for (int i = 0; i < 4; ++i) { v[i] = x[i] * scale * za[i] * sigmoidf_(za[i]); v[4 + i] = y[i] * scale * zb[i] * sigmoidf_(zb[i]); }
;             *(v4u*)(orow + d) = (v4u){cvtpk(v[0], v[1]), cvtpk(v[2], v[3]), cvtpk(v[4], v[5]), cvtpk(v[6], v[7])};
;         }
; }
	v_lshlrev_b32_e32 v14, 16, v82
	v_and_b32_e32 v15, 0xffff0000, v82
	v_mul_f32_e32 v26, 0xbfb8aa3b, v14
	v_pk_mul_f32 v[22:23], v[22:23], v[14:15]
	v_mul_f32_e32 v14, 0xbfb8aa3b, v15
	v_exp_f32_e32 v26, v26
	v_exp_f32_e32 v14, v14
	v_add_f32_e32 v26, 1.0, v26
	v_add_f32_e32 v14, 1.0, v14
	v_rcp_f32_e32 v30, v26
	v_rcp_f32_e32 v31, v14
	s_nop 0
	v_pk_mul_f32 v[14:15], v[22:23], v[30:31]
	v_lshlrev_b32_e32 v22, 16, v84
	v_and_b32_e32 v23, 0xffff0000, v84
	v_mul_f32_e32 v26, 0xbfb8aa3b, v22
	v_pk_mul_f32 v[24:25], v[24:25], v[22:23]
	v_mul_f32_e32 v22, 0xbfb8aa3b, v23
	v_exp_f32_e32 v26, v26
	v_exp_f32_e32 v22, v22
	v_add_f32_e32 v26, 1.0, v26
	v_add_f32_e32 v22, 1.0, v22
	v_rcp_f32_e32 v30, v26
	v_rcp_f32_e32 v31, v22
	s_nop 0
	v_pk_mul_f32 v[22:23], v[24:25], v[30:31]
	v_lshlrev_b32_e32 v24, 16, v83
	v_and_b32_e32 v25, 0xffff0000, v83
	v_mul_f32_e32 v26, 0xbfb8aa3b, v24
	v_pk_mul_f32 v[20:21], v[20:21], v[24:25]
	v_mul_f32_e32 v24, 0xbfb8aa3b, v25
	v_exp_f32_e32 v26, v26
	v_exp_f32_e32 v24, v24
	v_and_b32_e32 v25, 0xffff0000, v85
	v_add_f32_e32 v26, 1.0, v26
	v_add_f32_e32 v24, 1.0, v24
	v_rcp_f32_e32 v26, v26
	v_rcp_f32_e32 v27, v24
	v_lshlrev_b32_e32 v24, 16, v85
	v_pk_mul_f32 v[12:13], v[12:13], v[24:25]
	v_pk_mul_f32 v[20:21], v[20:21], v[26:27]
	v_mul_f32_e32 v26, 0xbfb8aa3b, v24
	v_mul_f32_e32 v24, 0xbfb8aa3b, v25
	v_exp_f32_e32 v26, v26
	v_exp_f32_e32 v24, v24
	v_add_f32_e32 v26, 1.0, v26
	v_add_f32_e32 v24, 1.0, v24
	v_rcp_f32_e32 v26, v26
	v_rcp_f32_e32 v27, v24
	s_nop 0
	v_pk_mul_f32 v[24:25], v[12:13], v[26:27]
	v_cvt_pk_bf16_f32 v12, v14, v15
	v_cvt_pk_bf16_f32 v13, v20, v21
	v_cvt_pk_bf16_f32 v14, v22, v23
	v_cvt_pk_bf16_f32 v15, v24, v25
	global_store_dwordx4 v[10:11], v[12:15], off offset:32
	s_waitcnt vmcnt(3)
	v_lshlrev_b32_e32 v20, 16, v86
	v_and_b32_e32 v21, 0xffff0000, v86
	v_mul_f32_e32 v12, 0xbfb8aa3b, v20
	v_exp_f32_e32 v12, v12
	v_pk_mul_f32 v[24:25], v[34:35], v[20:21]
	v_add_f32_e32 v12, 1.0, v12
	v_rcp_f32_e32 v22, v12
	v_mul_f32_e32 v12, 0xbfb8aa3b, v21
	v_exp_f32_e32 v12, v12
	s_nop 0
	v_add_f32_e32 v12, 1.0, v12
	v_rcp_f32_e32 v23, v12
	s_nop 0
	v_pk_mul_f32 v[20:21], v[24:25], v[22:23]
	v_lshlrev_b32_e32 v22, 16, v88
	v_mul_f32_e32 v12, 0xbfb8aa3b, v22
	v_exp_f32_e32 v12, v12
	v_and_b32_e32 v23, 0xffff0000, v88
	v_pk_mul_f32 v[18:19], v[18:19], v[22:23]
	v_add_f32_e32 v12, 1.0, v12
	v_rcp_f32_e32 v24, v12
	v_mul_f32_e32 v12, 0xbfb8aa3b, v23
	v_exp_f32_e32 v12, v12
	s_nop 0
	v_add_f32_e32 v12, 1.0, v12
	v_rcp_f32_e32 v25, v12
	v_lshlrev_b32_e32 v12, 16, v87
	v_and_b32_e32 v13, 0xffff0000, v87
	v_mul_f32_e32 v14, 0xbfb8aa3b, v12
	v_pk_mul_f32 v[18:19], v[18:19], v[24:25]
	v_pk_mul_f32 v[24:25], v[32:33], v[12:13]
	v_mul_f32_e32 v12, 0xbfb8aa3b, v13
	v_exp_f32_e32 v12, v12
	v_exp_f32_e32 v14, v14
	v_and_b32_e32 v13, 0xffff0000, v89
	v_add_f32_e32 v12, 1.0, v12
	v_add_f32_e32 v14, 1.0, v14
	v_rcp_f32_e32 v23, v12
	v_lshlrev_b32_e32 v12, 16, v89
	v_rcp_f32_e32 v22, v14
	v_mul_f32_e32 v14, 0xbfb8aa3b, v12
	v_pk_mul_f32 v[2:3], v[2:3], v[12:13]
	v_mul_f32_e32 v12, 0xbfb8aa3b, v13
	v_exp_f32_e32 v14, v14
	v_exp_f32_e32 v12, v12
	v_pk_mul_f32 v[22:23], v[24:25], v[22:23]
	v_add_f32_e32 v14, 1.0, v14
	v_add_f32_e32 v12, 1.0, v12
	v_rcp_f32_e32 v14, v14
	v_rcp_f32_e32 v15, v12
	v_cvt_pk_bf16_f32 v12, v20, v21
	v_cvt_pk_bf16_f32 v13, v22, v23
	v_pk_mul_f32 v[2:3], v[2:3], v[14:15]
	s_nop 0
	v_cvt_pk_bf16_f32 v15, v2, v3
	v_cvt_pk_bf16_f32 v14, v18, v19
	global_store_dwordx4 v[10:11], v[12:15], off offset:64
	s_waitcnt vmcnt(3)
	s_nop 0
	v_lshlrev_b32_e32 v12, 16, v90
	v_and_b32_e32 v13, 0xffff0000, v90
	v_mul_f32_e32 v0, 0xbfb8aa3b, v12
	v_exp_f32_e32 v0, v0
	v_pk_mul_f32 v[16:17], v[16:17], v[12:13]
	v_add_f32_e32 v0, 1.0, v0
	v_rcp_f32_e32 v14, v0
	v_mul_f32_e32 v0, 0xbfb8aa3b, v13
	v_exp_f32_e32 v0, v0
	s_nop 0
	v_add_f32_e32 v0, 1.0, v0
	v_rcp_f32_e32 v15, v0
	s_nop 0
	v_pk_mul_f32 v[12:13], v[16:17], v[14:15]
	v_lshlrev_b32_e32 v14, 16, v92
	v_mul_f32_e32 v0, 0xbfb8aa3b, v14
	v_exp_f32_e32 v0, v0
	v_and_b32_e32 v15, 0xffff0000, v92
	v_pk_mul_f32 v[8:9], v[8:9], v[14:15]
	v_add_f32_e32 v0, 1.0, v0
	v_rcp_f32_e32 v16, v0
	v_mul_f32_e32 v0, 0xbfb8aa3b, v15
	v_exp_f32_e32 v0, v0
	s_nop 0
	v_add_f32_e32 v0, 1.0, v0
	v_rcp_f32_e32 v17, v0
	v_lshlrev_b32_e32 v0, 16, v91
	v_and_b32_e32 v1, 0xffff0000, v91
	v_mul_f32_e32 v2, 0xbfb8aa3b, v0
	v_pk_mul_f32 v[6:7], v[6:7], v[0:1]
	v_mul_f32_e32 v0, 0xbfb8aa3b, v1
	v_exp_f32_e32 v0, v0
	v_exp_f32_e32 v2, v2
	v_and_b32_e32 v1, 0xffff0000, v93
	v_pk_mul_f32 v[8:9], v[8:9], v[16:17]
	v_add_f32_e32 v0, 1.0, v0
	v_add_f32_e32 v2, 1.0, v2
	v_rcp_f32_e32 v15, v0
	v_lshlrev_b32_e32 v0, 16, v93
	v_rcp_f32_e32 v14, v2
	v_mul_f32_e32 v2, 0xbfb8aa3b, v0
	v_pk_mul_f32 v[4:5], v[4:5], v[0:1]
	v_mul_f32_e32 v0, 0xbfb8aa3b, v1
	v_exp_f32_e32 v2, v2
	v_exp_f32_e32 v0, v0
	v_pk_mul_f32 v[6:7], v[6:7], v[14:15]
	v_add_f32_e32 v2, 1.0, v2
	v_add_f32_e32 v0, 1.0, v0
	v_rcp_f32_e32 v2, v2
	v_rcp_f32_e32 v3, v0
	v_cvt_pk_bf16_f32 v0, v12, v13
	v_cvt_pk_bf16_f32 v1, v6, v7
	v_pk_mul_f32 v[4:5], v[4:5], v[2:3]
	v_cvt_pk_bf16_f32 v2, v8, v9
	v_cvt_pk_bf16_f32 v3, v4, v5
	global_store_dwordx4 v[10:11], v[0:3], off offset:96
	s_barrier
	s_cbranch_scc1 .LBB0_1152

; __device__ __forceinline__ int fresh_tid(int wv) { return wv * 64 + fresh_lane(); }
; __device__ __forceinline__ unsigned cvtpk(float lo, float hi) { f32x2_t v = {lo, hi}; bf16x2_t b = __builtin_convertvector(v, bf16x2_t); return __builtin_bit_cast(unsigned, b); }
; __device__ __forceinline__ float sigmoidf_(float x) { return __builtin_amdgcn_rcpf(1.f + fexp2(-1.4426950408889634f * x)); }
; __device__ __forceinline__ void attn_epilogue(const f32x16& a0, const f32x16& a1, float scale, const bf16* zrow, bf16* orow, int hi) {
; #pragma unroll
;     for (int db = 0; db < 2; ++db)
; #pragma unroll
;         for (int p = 0; p < 2; ++p) {
;             const f32x16& o = db ? a1 : a0;
;             float x[4], y[4];
; #pragma unroll
;             for (int i = 0; i < 4; ++i) {
;                 auto rr = __builtin_amdgcn_permlane32_swap(__float_as_uint(o[8 * p + i]), __float_as_uint(o[8 * p + 4 + i]), false, false);
;                 x[i] = __uint_as_float(rr[0]); y[i] = __uint_as_float(rr[1]);
;             }
;             const int d = 32 * db + 8 * (2 * p + hi);
;             const v4u zz = *(const v4u*)(zrow + d);
;             f32x4 za, zb; unpack8(zz, za, zb);
;             float v[8];
; #pragma unroll
;             for (int i = 0; i < 4; ++i) { v[i] = x[i] * scale * za[i] * sigmoidf_(za[i]); v[4 + i] = y[i] * scale * zb[i] * sigmoidf_(zb[i]); }
;             *(v4u*)(orow + d) = (v4u){cvtpk(v[0], v[1]), cvtpk(v[2], v[3]), cvtpk(v[4], v[5]), cvtpk(v[6], v[7])};
;         }
; }
; __device__ __forceinline__ void nsa_unit(const int wv, LAS unsigned char* lds, int b, int g, int c, const bf16* Y, const bf16* KCMP, const bf16* VCMP, const float* gates, bf16* OG) {
;     ...
;         const float l = swap_sum(o2[0]); const float s = g2 / l;
; #pragma unroll
;         for (int r = 0; r < 16; ++r) { acc0[r] = accs[r * 512] + s * o0[r]; acc1[r] = accs[(16 + r) * 512] + s * o1[r]; }
;     }
;     const int tid3 = fresh_tid(wv); const int hi3 = (tid3 >> 5) & 1, hh3 = 4 * g + (tid3 >> 7); const size_t row3 = (size_t)b * T + 64 * c + 32 * ((tid3 >> 6) & 1) + (tid3 & 31);
;     attn_epilogue(acc0, acc1, 1.0f, Y + row3 * NSA_LDY + 2048 + hh3 * 64, OG + row3 * D + hh3 * 64, hi3);
.LBB0_996:
	v_mov_b32_e32 v32, v34
	s_nop 1
	v_permlane32_swap_b32_e32 v34, v32
	v_add_f32_e32 v32, v34, v32
	v_div_scale_f32 v33, s[0:1], v32, v32, v184
	v_rcp_f32_e32 v34, v33
	ds_read2st64_b32 v[40:41], v185 offset0:48 offset1:56
	ds_read2st64_b32 v[38:39], v185 offset1:8
	ds_read2st64_b32 v[42:43], v185 offset0:32 offset1:40
	v_fma_f32 v35, -v33, v34, 1.0
	v_fmac_f32_e32 v34, v35, v34
	v_div_scale_f32 v35, vcc, v184, v32, v184
	v_mul_f32_e32 v36, v35, v34
	v_fma_f32 v37, -v33, v36, v35
	v_fmac_f32_e32 v36, v37, v34
	v_fma_f32 v33, -v33, v36, v35
	v_div_fmas_f32 v33, v33, v34, v36
	ds_read2st64_b32 v[34:35], v185 offset0:128 offset1:136
	v_div_fixup_f32 v44, v33, v32, v184
	ds_read2st64_b32 v[36:37], v185 offset0:16 offset1:24
	ds_read2st64_b32 v[32:33], v185 offset0:144 offset1:152
	s_waitcnt lgkmcnt(5)
	v_fma_f32 v40, v6, v44, v40
	s_waitcnt lgkmcnt(2)
	v_fma_f32 v34, v16, v44, v34
	v_fmac_f32_e32 v35, v17, v44
	ds_read2st64_b32 v[16:17], v185 offset0:192 offset1:200
	s_waitcnt lgkmcnt(2)
	v_fma_f32 v36, v2, v44, v36
	v_fmac_f32_e32 v37, v3, v44
	ds_read2st64_b32 v[2:3], v185 offset0:176 offset1:184
	s_waitcnt lgkmcnt(2)
	v_fma_f32 v32, v18, v44, v32
	s_waitcnt lgkmcnt(1)
	v_fma_f32 v16, v24, v44, v16
	v_fmac_f32_e32 v17, v25, v44
	ds_read2st64_b32 v[24:25], v185 offset0:96 offset1:104
	v_fmac_f32_e32 v33, v19, v44
	ds_read2st64_b32 v[18:19], v185 offset0:160 offset1:168
	s_waitcnt lgkmcnt(2)
	v_fma_f32 v2, v22, v44, v2
	v_fmac_f32_e32 v41, v7, v44
	v_fmac_f32_e32 v3, v23, v44
	ds_read2st64_b32 v[22:23], v185 offset0:64 offset1:72
	ds_read2st64_b32 v[6:7], v185 offset0:208 offset1:216
	s_waitcnt lgkmcnt(3)
	v_fma_f32 v24, v12, v44, v24
	v_fmac_f32_e32 v25, v13, v44
	ds_read2st64_b32 v[12:13], v185 offset0:112 offset1:120
	v_fma_f32 v38, v0, v44, v38
	v_fma_f32 v42, v4, v44, v42
	s_waitcnt lgkmcnt(3)
	v_fma_f32 v18, v20, v44, v18
	v_fmac_f32_e32 v43, v5, v44
	v_fmac_f32_e32 v19, v21, v44
	s_waitcnt lgkmcnt(2)
	v_fma_f32 v22, v8, v44, v22
	v_fmac_f32_e32 v23, v9, v44
	ds_read2st64_b32 v[20:21], v185 offset0:80 offset1:88
	s_waitcnt lgkmcnt(2)
	v_fma_f32 v6, v26, v44, v6
	ds_read2st64_b32 v[8:9], v185 offset0:224 offset1:232
	ds_read2st64_b32 v[4:5], v185 offset0:240 offset1:248
	v_mbcnt_lo_u32_b32 v26, -1, 0
	v_mbcnt_hi_u32_b32 v26, -1, v26
	s_waitcnt lgkmcnt(3)
	v_fma_f32 v12, v14, v44, v12
	v_add_u32_e32 v0, s83, v26
	v_ashrrev_i32_e32 v14, 7, v0
	v_lshrrev_b32_e32 v0, 1, v0
	v_fmac_f32_e32 v39, v1, v44
	v_and_b32_e32 v0, 32, v0
	v_and_b32_e32 v1, 31, v26
	v_readlane_b32 s0, v254, 58
	s_waitcnt lgkmcnt(2)
	v_fma_f32 v20, v10, v44, v20
	v_fmac_f32_e32 v21, v11, v44
	v_or3_b32 v0, s0, v0, v1
	v_readlane_b32 s0, v254, 27
	v_readlane_b32 s1, v254, 28
	v_readlane_b32 s4, v254, 59
	v_fmac_f32_e32 v13, v15, v44
	v_mov_b64_e32 v[10:11], s[0:1]
	v_mad_u64_u32 v[10:11], s[0:1], v0, s84, v[10:11]
	v_readlane_b32 s0, v254, 21
	v_mov_b32_e32 v1, s4
	v_lshlrev_b64 v[0:1], 11, v[0:1]
	v_add_lshl_u32 v14, v14, s0, 6
	v_readlane_b32 s0, v254, 25
	v_ashrrev_i32_e32 v15, 31, v14
	v_readlane_b32 s1, v254, 26
	v_mad_i32_i24 v11, s4, v246, v11
	v_lshlrev_b64 v[14:15], 1, v[14:15]
	v_lshl_add_u64 v[0:1], s[0:1], 0, v[0:1]
	v_lshl_add_u64 v[10:11], v[10:11], 0, v[14:15]
	v_lshl_add_u64 v[14:15], v[0:1], 0, v[14:15]
	v_lshrrev_b32_e32 v0, 1, v26
	v_and_b32_e32 v114, 16, v0
	v_lshl_add_u64 v[10:11], v[10:11], 0, v[114:115]
	s_mov_b64 s[0:1], 0x1000
	v_lshl_add_u64 v[0:1], v[10:11], 0, s[0:1]
	s_movk_i32 s0, 0x1000
	v_add_co_u32_e32 v10, vcc, s0, v10
	v_fmac_f32_e32 v7, v27, v44
	s_nop 0
	v_addc_co_u32_e32 v11, vcc, 0, v11, vcc
	s_waitcnt lgkmcnt(1)
	v_fma_f32 v8, v28, v44, v8
	v_fmac_f32_e32 v9, v29, v44
	global_load_dwordx4 v[26:29], v[10:11], off
	global_load_dwordx4 v[82:85], v[0:1], off offset:32
	global_load_dwordx4 v[86:89], v[0:1], off offset:64
	global_load_dwordx4 v[90:93], v[0:1], off offset:96
	v_permlane32_swap_b32_e32 v38, v42
	v_permlane32_swap_b32_e32 v39, v43
	s_waitcnt lgkmcnt(0)
	v_fma_f32 v4, v30, v44, v4
	v_fmac_f32_e32 v5, v31, v44
	v_permlane32_swap_b32_e32 v36, v40
	v_permlane32_swap_b32_e32 v37, v41
	v_permlane32_swap_b32_e32 v22, v24
	v_permlane32_swap_b32_e32 v23, v25
	v_permlane32_swap_b32_e32 v20, v12
	v_permlane32_swap_b32_e32 v21, v13
	v_permlane32_swap_b32_e32 v34, v18
	v_permlane32_swap_b32_e32 v35, v19
	v_permlane32_swap_b32_e32 v32, v2
	v_permlane32_swap_b32_e32 v33, v3
	v_permlane32_swap_b32_e32 v16, v8
	v_permlane32_swap_b32_e32 v17, v9
	v_permlane32_swap_b32_e32 v6, v4
	v_permlane32_swap_b32_e32 v7, v5
	s_movk_i32 s0, 0x4100
	s_waitcnt vmcnt(3)
	v_lshlrev_b32_e32 v10, 16, v26
	v_and_b32_e32 v11, 0xffff0000, v26
	v_mul_f32_e32 v26, 0xbfb8aa3b, v10
	v_pk_mul_f32 v[38:39], v[38:39], v[10:11]
	v_mul_f32_e32 v10, 0xbfb8aa3b, v11
	v_exp_f32_e32 v26, v26
	v_exp_f32_e32 v10, v10
	v_add_f32_e32 v26, 1.0, v26
	v_add_f32_e32 v10, 1.0, v10
	v_rcp_f32_e32 v30, v26
	v_rcp_f32_e32 v31, v10
	s_nop 0
	v_pk_mul_f32 v[10:11], v[38:39], v[30:31]
	v_lshlrev_b32_e32 v30, 16, v28
	v_mul_f32_e32 v26, 0xbfb8aa3b, v30
	v_exp_f32_e32 v26, v26
	v_and_b32_e32 v31, 0xffff0000, v28
	v_pk_mul_f32 v[42:43], v[42:43], v[30:31]
	v_add_f32_e32 v26, 1.0, v26
	v_rcp_f32_e32 v38, v26
	v_mul_f32_e32 v26, 0xbfb8aa3b, v31
	v_exp_f32_e32 v26, v26
	s_nop 0
	v_add_f32_e32 v26, 1.0, v26
	v_rcp_f32_e32 v39, v26
	v_lshlrev_b32_e32 v26, 16, v27
	v_and_b32_e32 v27, 0xffff0000, v27
	v_mul_f32_e32 v28, 0xbfb8aa3b, v26
	v_pk_mul_f32 v[36:37], v[36:37], v[26:27]
	v_mul_f32_e32 v26, 0xbfb8aa3b, v27
	v_exp_f32_e32 v28, v28
	v_exp_f32_e32 v26, v26
	v_pk_mul_f32 v[30:31], v[42:43], v[38:39]
	v_and_b32_e32 v27, 0xffff0000, v29
	v_add_f32_e32 v28, 1.0, v28
	v_add_f32_e32 v26, 1.0, v26
	v_rcp_f32_e32 v38, v28
	v_rcp_f32_e32 v39, v26
	v_lshlrev_b32_e32 v26, 16, v29
	v_mul_f32_e32 v28, 0xbfb8aa3b, v26
	v_exp_f32_e32 v28, v28
	v_pk_mul_f32 v[36:37], v[36:37], v[38:39]
	v_pk_mul_f32 v[38:39], v[40:41], v[26:27]
	v_mul_f32_e32 v26, 0xbfb8aa3b, v27
	v_exp_f32_e32 v26, v26
	v_add_f32_e32 v28, 1.0, v28
	v_rcp_f32_e32 v28, v28
	v_cvt_pk_bf16_f32 v27, v36, v37
	v_add_f32_e32 v26, 1.0, v26
	v_rcp_f32_e32 v29, v26
	v_cvt_pk_bf16_f32 v26, v10, v11
	v_lshl_add_u64 v[10:11], v[14:15], 0, v[114:115]
	v_pk_mul_f32 v[38:39], v[38:39], v[28:29]
	v_cvt_pk_bf16_f32 v28, v30, v31
	v_cvt_pk_bf16_f32 v29, v38, v39
	global_store_dwordx4 v[10:11], v[26:29], off
	s_waitcnt vmcnt(3)
; __device__ __forceinline__ unsigned cvtpk(float lo, float hi) { f32x2_t v = {lo, hi}; bf16x2_t b = __builtin_convertvector(v, bf16x2_t); return __builtin_bit_cast(unsigned, b); }
; __device__ __forceinline__ float sigmoidf_(float x) { return __builtin_amdgcn_rcpf(1.f + fexp2(-1.4426950408889634f * x)); }
; __device__ __forceinline__ void attn_epilogue(const f32x16& a0, const f32x16& a1, float scale, const bf16* zrow, bf16* orow, int hi) {
; #pragma unroll
;     for (int db = 0; db < 2; ++db)
; #pragma unroll
;         for (int p = 0; p < 2; ++p) {
;             const f32x16& o = db ? a1 : a0;
;             float x[4], y[4];
; #pragma unroll
;             for (int i = 0; i < 4; ++i) {
;                 auto rr = __builtin_amdgcn_permlane32_swap(__float_as_uint(o[8 * p + i]), __float_as_uint(o[8 * p + 4 + i]), false, false);
;                 x[i] = __uint_as_float(rr[0]); y[i] = __uint_as_float(rr[1]);
;             }
;             const int d = 32 * db + 8 * (2 * p + hi);
;             const v4u zz = *(const v4u*)(zrow + d);
;             f32x4 za, zb; unpack8(zz, za, zb);
;             float v[8];
; #pragma unroll
;             for (int i = 0; i < 4; ++i) { v[i] = x[i] * scale * za[i] * sigmoidf_(za[i]); v[4 + i] = y[i] * scale * zb[i] * sigmoidf_(zb[i]); }
;             *(v4u*)(orow + d) = (v4u){cvtpk(v[0], v[1]), cvtpk(v[2], v[3]), cvtpk(v[4], v[5]), cvtpk(v[6], v[7])};
;         }
; }
; __device__ __forceinline__ void nsa_unit(const int wv, LAS unsigned char* lds, int b, int g, int c, const bf16* Y, const bf16* KCMP, const bf16* VCMP, const float* gates, bf16* OG) {
;     ...
;     for (int i = tid; i < 4 * 64 * 65; i += NTHREADS) imph[i] = 0.f;
	v_lshlrev_b32_e32 v14, 16, v82
	v_and_b32_e32 v15, 0xffff0000, v82
	v_mul_f32_e32 v26, 0xbfb8aa3b, v14
	v_pk_mul_f32 v[22:23], v[22:23], v[14:15]
	v_mul_f32_e32 v14, 0xbfb8aa3b, v15
	v_exp_f32_e32 v26, v26
	v_exp_f32_e32 v14, v14
	v_add_f32_e32 v26, 1.0, v26
	v_add_f32_e32 v14, 1.0, v14
	v_rcp_f32_e32 v30, v26
	v_rcp_f32_e32 v31, v14
	s_nop 0
	v_pk_mul_f32 v[14:15], v[22:23], v[30:31]
	v_lshlrev_b32_e32 v22, 16, v84
	v_and_b32_e32 v23, 0xffff0000, v84
	v_mul_f32_e32 v26, 0xbfb8aa3b, v22
	v_pk_mul_f32 v[24:25], v[24:25], v[22:23]
	v_mul_f32_e32 v22, 0xbfb8aa3b, v23
	v_exp_f32_e32 v26, v26
	v_exp_f32_e32 v22, v22
	v_add_f32_e32 v26, 1.0, v26
	v_add_f32_e32 v22, 1.0, v22
	v_rcp_f32_e32 v30, v26
	v_rcp_f32_e32 v31, v22
	s_nop 0
	v_pk_mul_f32 v[22:23], v[24:25], v[30:31]
	v_lshlrev_b32_e32 v24, 16, v83
	v_and_b32_e32 v25, 0xffff0000, v83
	v_mul_f32_e32 v26, 0xbfb8aa3b, v24
	v_pk_mul_f32 v[20:21], v[20:21], v[24:25]
	v_mul_f32_e32 v24, 0xbfb8aa3b, v25
	v_exp_f32_e32 v26, v26
	v_exp_f32_e32 v24, v24
	v_and_b32_e32 v25, 0xffff0000, v85
	v_add_f32_e32 v26, 1.0, v26
	v_add_f32_e32 v24, 1.0, v24
	v_rcp_f32_e32 v26, v26
	v_rcp_f32_e32 v27, v24
	v_lshlrev_b32_e32 v24, 16, v85
	v_pk_mul_f32 v[12:13], v[12:13], v[24:25]
	v_pk_mul_f32 v[20:21], v[20:21], v[26:27]
	v_mul_f32_e32 v26, 0xbfb8aa3b, v24
	v_mul_f32_e32 v24, 0xbfb8aa3b, v25
	v_exp_f32_e32 v26, v26
	v_exp_f32_e32 v24, v24
	v_add_f32_e32 v26, 1.0, v26
	v_add_f32_e32 v24, 1.0, v24
	v_rcp_f32_e32 v26, v26
	v_rcp_f32_e32 v27, v24
	s_nop 0
	v_pk_mul_f32 v[24:25], v[12:13], v[26:27]
	v_cvt_pk_bf16_f32 v12, v14, v15
	v_cvt_pk_bf16_f32 v13, v20, v21
	v_cvt_pk_bf16_f32 v14, v22, v23
	v_cvt_pk_bf16_f32 v15, v24, v25
	global_store_dwordx4 v[10:11], v[12:15], off offset:32
	s_waitcnt vmcnt(3)
	v_lshlrev_b32_e32 v20, 16, v86
	v_and_b32_e32 v21, 0xffff0000, v86
	v_mul_f32_e32 v12, 0xbfb8aa3b, v20
	v_exp_f32_e32 v12, v12
	v_pk_mul_f32 v[24:25], v[34:35], v[20:21]
	v_add_f32_e32 v12, 1.0, v12
	v_rcp_f32_e32 v22, v12
	v_mul_f32_e32 v12, 0xbfb8aa3b, v21
	v_exp_f32_e32 v12, v12
	s_nop 0
	v_add_f32_e32 v12, 1.0, v12
	v_rcp_f32_e32 v23, v12
	s_nop 0
	v_pk_mul_f32 v[20:21], v[24:25], v[22:23]
	v_lshlrev_b32_e32 v22, 16, v88
	v_mul_f32_e32 v12, 0xbfb8aa3b, v22
	v_exp_f32_e32 v12, v12
	v_and_b32_e32 v23, 0xffff0000, v88
	v_pk_mul_f32 v[18:19], v[18:19], v[22:23]
	v_add_f32_e32 v12, 1.0, v12
	v_rcp_f32_e32 v24, v12
	v_mul_f32_e32 v12, 0xbfb8aa3b, v23
	v_exp_f32_e32 v12, v12
	s_nop 0
	v_add_f32_e32 v12, 1.0, v12
	v_rcp_f32_e32 v25, v12
	v_lshlrev_b32_e32 v12, 16, v87
	v_and_b32_e32 v13, 0xffff0000, v87
	v_mul_f32_e32 v14, 0xbfb8aa3b, v12
	v_pk_mul_f32 v[18:19], v[18:19], v[24:25]
	v_pk_mul_f32 v[24:25], v[32:33], v[12:13]
	v_mul_f32_e32 v12, 0xbfb8aa3b, v13
	v_exp_f32_e32 v12, v12
	v_exp_f32_e32 v14, v14
	v_and_b32_e32 v13, 0xffff0000, v89
	v_add_f32_e32 v12, 1.0, v12
	v_add_f32_e32 v14, 1.0, v14
	v_rcp_f32_e32 v23, v12
	v_lshlrev_b32_e32 v12, 16, v89
	v_rcp_f32_e32 v22, v14
	v_mul_f32_e32 v14, 0xbfb8aa3b, v12
	v_pk_mul_f32 v[2:3], v[2:3], v[12:13]
	v_mul_f32_e32 v12, 0xbfb8aa3b, v13
	v_exp_f32_e32 v14, v14
	v_exp_f32_e32 v12, v12
	v_pk_mul_f32 v[22:23], v[24:25], v[22:23]
	v_add_f32_e32 v14, 1.0, v14
	v_add_f32_e32 v12, 1.0, v12
	v_rcp_f32_e32 v14, v14
	v_rcp_f32_e32 v15, v12
	v_cvt_pk_bf16_f32 v12, v20, v21
	v_cvt_pk_bf16_f32 v13, v22, v23
	v_pk_mul_f32 v[2:3], v[2:3], v[14:15]
	s_nop 0
	v_cvt_pk_bf16_f32 v15, v2, v3
	v_cvt_pk_bf16_f32 v14, v18, v19
	global_store_dwordx4 v[10:11], v[12:15], off offset:64
	s_waitcnt vmcnt(3)
	s_nop 0
	v_lshlrev_b32_e32 v12, 16, v90
	v_and_b32_e32 v13, 0xffff0000, v90
	v_mul_f32_e32 v0, 0xbfb8aa3b, v12
	v_exp_f32_e32 v0, v0
	v_pk_mul_f32 v[16:17], v[16:17], v[12:13]
	v_add_f32_e32 v0, 1.0, v0
	v_rcp_f32_e32 v14, v0
	v_mul_f32_e32 v0, 0xbfb8aa3b, v13
	v_exp_f32_e32 v0, v0
	s_nop 0
	v_add_f32_e32 v0, 1.0, v0
	v_rcp_f32_e32 v15, v0
	s_nop 0
	v_pk_mul_f32 v[12:13], v[16:17], v[14:15]
	v_lshlrev_b32_e32 v14, 16, v92
	v_mul_f32_e32 v0, 0xbfb8aa3b, v14
	v_exp_f32_e32 v0, v0
	v_and_b32_e32 v15, 0xffff0000, v92
	v_pk_mul_f32 v[8:9], v[8:9], v[14:15]
	v_add_f32_e32 v0, 1.0, v0
	v_rcp_f32_e32 v16, v0
	v_mul_f32_e32 v0, 0xbfb8aa3b, v15
	v_exp_f32_e32 v0, v0
	s_nop 0
	v_add_f32_e32 v0, 1.0, v0
	v_rcp_f32_e32 v17, v0
	v_lshlrev_b32_e32 v0, 16, v91
	v_and_b32_e32 v1, 0xffff0000, v91
	v_mul_f32_e32 v2, 0xbfb8aa3b, v0
	v_pk_mul_f32 v[6:7], v[6:7], v[0:1]
	v_mul_f32_e32 v0, 0xbfb8aa3b, v1
	v_exp_f32_e32 v0, v0
	v_exp_f32_e32 v2, v2
	v_and_b32_e32 v1, 0xffff0000, v93
	v_pk_mul_f32 v[8:9], v[8:9], v[16:17]
	v_add_f32_e32 v0, 1.0, v0
	v_add_f32_e32 v2, 1.0, v2
	v_rcp_f32_e32 v15, v0
	v_lshlrev_b32_e32 v0, 16, v93
	v_rcp_f32_e32 v14, v2
	v_mul_f32_e32 v2, 0xbfb8aa3b, v0
	v_pk_mul_f32 v[4:5], v[4:5], v[0:1]
	v_mul_f32_e32 v0, 0xbfb8aa3b, v1
	v_exp_f32_e32 v2, v2
	v_exp_f32_e32 v0, v0
	v_pk_mul_f32 v[6:7], v[6:7], v[14:15]
	v_add_f32_e32 v2, 1.0, v2
	v_add_f32_e32 v0, 1.0, v0
	v_rcp_f32_e32 v2, v2
	v_rcp_f32_e32 v3, v0
	v_cvt_pk_bf16_f32 v0, v12, v13
	v_cvt_pk_bf16_f32 v1, v6, v7
	v_pk_mul_f32 v[4:5], v[4:5], v[2:3]
	v_cvt_pk_bf16_f32 v2, v8, v9
	v_cvt_pk_bf16_f32 v3, v4, v5
	global_store_dwordx4 v[10:11], v[0:3], off offset:96
	s_barrier
	v_mbcnt_lo_u32_b32 v33, -1, 0
	v_mbcnt_hi_u32_b32 v33, -1, v33
	s_nop 0
	v_add_u32_e32 v160, s83, v33
	v_cmp_gt_i32_e32 vcc, s0, v160
	s_and_saveexec_b64 s[4:5], vcc
	s_movk_i32 s8, 0x3eff
	s_cbranch_execz .LBB0_999
	v_readlane_b32 s0, v254, 3
	s_mov_b64 s[6:7], 0
	s_nop 0
	v_add_u32_e32 v0, s0, v33
	v_readlane_b32 s0, v254, 4
	s_nop 1
	v_lshl_add_u32 v1, v33, 2, s0

; __device__ __forceinline__ unsigned cvtpk(float lo, float hi) { f32x2_t v = {lo, hi}; bf16x2_t b = __builtin_convertvector(v, bf16x2_t); return __builtin_bit_cast(unsigned, b); }
; __device__ __forceinline__ float sigmoidf_(float x) { return __builtin_amdgcn_rcpf(1.f + fexp2(-1.4426950408889634f * x)); }
; __device__ __forceinline__ float swap_sum(float v) { auto rr = __builtin_amdgcn_permlane32_swap(__float_as_uint(v), __float_as_uint(v), false, false); return __uint_as_float(rr[0]) + __uint_as_float(rr[1]); }
; __device__ __forceinline__ void attn_epilogue(const f32x16& a0, const f32x16& a1, float scale, const bf16* zrow, bf16* orow, int hi) {
; #pragma unroll
;     for (int db = 0; db < 2; ++db)
; #pragma unroll
;         for (int p = 0; p < 2; ++p) {
;             const f32x16& o = db ? a1 : a0;
;             float x[4], y[4];
; #pragma unroll
;             for (int i = 0; i < 4; ++i) {
;                 auto rr = __builtin_amdgcn_permlane32_swap(__float_as_uint(o[8 * p + i]), __float_as_uint(o[8 * p + 4 + i]), false, false);
;                 x[i] = __uint_as_float(rr[0]); y[i] = __uint_as_float(rr[1]);
;             }
;             const int d = 32 * db + 8 * (2 * p + hi);
;             const v4u zz = *(const v4u*)(zrow + d);
;             f32x4 za, zb; unpack8(zz, za, zb);
;             float v[8];
; #pragma unroll
;             for (int i = 0; i < 4; ++i) { v[i] = x[i] * scale * za[i] * sigmoidf_(za[i]); v[4 + i] = y[i] * scale * zb[i] * sigmoidf_(zb[i]); }
;             *(v4u*)(orow + d) = (v4u){cvtpk(v[0], v[1]), cvtpk(v[2], v[3]), cvtpk(v[4], v[5]), cvtpk(v[6], v[7])};
;         }
; }
; __device__ __forceinline__ void moba_unit(const int wv, LAS unsigned char* lds, int b, int h, int qb, const bf16* Y, const float* kmean_l, bf16* OG) {
;     ...
;     const float l = swap_sum(o2[0]); const float il = 1.0f / l;
;     attn_epilogue(o0, o1, il, Y + row * MOBA_LDY + 3072 + h * 64, OG + row * D + h * 64, hi);
.LBB0_1155:
	s_setprio 0
	s_nop 1
	v_mov_b32_e32 v33, v32
	s_nop 1
	v_permlane32_swap_b32_e32 v32, v33
	v_add_f32_e32 v32, v32, v33
	v_div_scale_f32 v33, s[0:1], v32, v32, 1.0
	v_rcp_f32_e32 v34, v33
	v_readlane_b32 s0, v254, 9
	v_readlane_b32 s4, v254, 25
	v_readlane_b32 s1, v254, 10
	v_fma_f32 v35, -v33, v34, 1.0
	v_fmac_f32_e32 v34, v35, v34
	v_div_scale_f32 v35, vcc, 1.0, v32, 1.0
	v_mul_f32_e32 v36, v35, v34
	v_fma_f32 v37, -v33, v36, v35
	v_fmac_f32_e32 v36, v37, v34
	v_fma_f32 v33, -v33, v36, v35
	v_div_fmas_f32 v33, v33, v34, v36
	v_lshlrev_b64 v[36:37], 11, v[112:113]
	v_readlane_b32 s5, v254, 26
	v_lshl_add_u64 v[34:35], v[152:153], 0, s[0:1]
	v_lshlrev_b32_e32 v114, 1, v114
	v_lshl_add_u64 v[36:37], s[4:5], 0, v[36:37]
	v_lshl_add_u64 v[38:39], v[36:37], 0, s[0:1]
	v_lshl_add_u64 v[34:35], v[34:35], 0, v[114:115]
	s_mov_b64 s[0:1], 0x1800
	v_mov_b32_e32 v40, v20
	v_mov_b32_e32 v41, v21
	v_lshl_add_u64 v[20:21], v[34:35], 0, s[0:1]
	s_movk_i32 s0, 0x1000
	v_add_co_u32_e32 v34, vcc, s0, v34
	v_div_fixup_f32 v32, v33, v32, 1.0
	s_nop 0
	v_addc_co_u32_e32 v35, vcc, 0, v35, vcc
	global_load_dwordx4 v[34:37], v[34:35], off offset:2048
	global_load_dwordx4 v[96:99], v[20:21], off offset:32
	global_load_dwordx4 v[100:103], v[20:21], off offset:64
	global_load_dwordx4 v[104:107], v[20:21], off offset:96
	v_permlane32_swap_b32_e32 v16, v40
	v_permlane32_swap_b32_e32 v17, v41
	v_permlane32_swap_b32_e32 v18, v22
	v_permlane32_swap_b32_e32 v19, v23
	s_add_i32 s27, s27, 1
	s_addk_i32 s23, 0x80
	s_cmp_eq_u32 s27, 8
	s_movk_i32 s35, 0x3eff
	s_waitcnt vmcnt(3)
	v_lshlrev_b32_e32 v42, 16, v34
	v_mul_f32_e32 v33, 0xbfb8aa3b, v42
	v_exp_f32_e32 v33, v33
	v_and_b32_e32 v43, 0xffff0000, v34
	v_lshlrev_b32_e32 v34, 16, v35
	v_and_b32_e32 v35, 0xffff0000, v35
	v_add_f32_e32 v33, 1.0, v33
	v_rcp_f32_e32 v44, v33
	v_pk_mul_f32 v[16:17], v[32:33], v[16:17] op_sel_hi:[0,1]
	v_mul_f32_e32 v33, 0xbfb8aa3b, v43
	v_exp_f32_e32 v33, v33
	v_pk_mul_f32 v[16:17], v[16:17], v[42:43]
	v_lshlrev_b32_e32 v42, 16, v36
	v_and_b32_e32 v43, 0xffff0000, v36
	v_add_f32_e32 v33, 1.0, v33
	v_rcp_f32_e32 v45, v33
	v_mul_f32_e32 v33, 0xbfb8aa3b, v42
	v_exp_f32_e32 v33, v33
	v_pk_mul_f32 v[16:17], v[16:17], v[44:45]
	v_add_f32_e32 v33, 1.0, v33
	v_rcp_f32_e32 v44, v33
	v_pk_mul_f32 v[40:41], v[32:33], v[40:41] op_sel_hi:[0,1]
	v_mul_f32_e32 v33, 0xbfb8aa3b, v43
	v_exp_f32_e32 v33, v33
	v_pk_mul_f32 v[40:41], v[40:41], v[42:43]
	v_add_f32_e32 v33, 1.0, v33
	v_rcp_f32_e32 v45, v33
	v_mul_f32_e32 v33, 0xbfb8aa3b, v34
	v_exp_f32_e32 v33, v33
	v_pk_mul_f32 v[40:41], v[40:41], v[44:45]
	v_add_f32_e32 v33, 1.0, v33
	v_rcp_f32_e32 v42, v33
	v_pk_mul_f32 v[18:19], v[32:33], v[18:19] op_sel_hi:[0,1]
	v_mul_f32_e32 v33, 0xbfb8aa3b, v35
	v_exp_f32_e32 v33, v33
	v_pk_mul_f32 v[18:19], v[18:19], v[34:35]
	v_lshlrev_b32_e32 v34, 16, v37
	v_and_b32_e32 v35, 0xffff0000, v37
	v_add_f32_e32 v33, 1.0, v33
	v_rcp_f32_e32 v43, v33
	v_mul_f32_e32 v33, 0xbfb8aa3b, v34
	v_exp_f32_e32 v33, v33
	v_pk_mul_f32 v[18:19], v[18:19], v[42:43]
	v_add_f32_e32 v33, 1.0, v33
	v_rcp_f32_e32 v36, v33
	v_pk_mul_f32 v[22:23], v[32:33], v[22:23] op_sel_hi:[0,1]
	v_mul_f32_e32 v33, 0xbfb8aa3b, v35
	v_exp_f32_e32 v33, v33
	v_pk_mul_f32 v[22:23], v[22:23], v[34:35]
	v_cvt_pk_bf16_f32 v35, v18, v19
	v_mov_b32_e32 v18, v30
	v_add_f32_e32 v33, 1.0, v33
	v_rcp_f32_e32 v37, v33
	v_mov_b32_e32 v19, v31
	v_cvt_pk_bf16_f32 v34, v16, v17
	v_lshl_add_u64 v[16:17], v[38:39], 0, v[114:115]
	v_pk_mul_f32 v[22:23], v[22:23], v[36:37]
	v_cvt_pk_bf16_f32 v36, v40, v41
	v_cvt_pk_bf16_f32 v37, v22, v23
	v_mov_b32_e32 v22, v28
	v_mov_b32_e32 v23, v29
	v_permlane32_swap_b32_e32 v24, v22
	global_store_dwordx4 v[16:17], v[34:37], off
	v_permlane32_swap_b32_e32 v25, v23
	v_pk_mul_f32 v[24:25], v[32:33], v[24:25] op_sel_hi:[0,1]
	v_pk_mul_f32 v[22:23], v[32:33], v[22:23] op_sel_hi:[0,1]
	v_permlane32_swap_b32_e32 v26, v18
	v_permlane32_swap_b32_e32 v27, v19
	v_pk_mul_f32 v[26:27], v[32:33], v[26:27] op_sel_hi:[0,1]
	v_pk_mul_f32 v[18:19], v[32:33], v[18:19] op_sel_hi:[0,1]
	s_waitcnt vmcnt(3)
; __device__ __forceinline__ unsigned cvtpk(float lo, float hi) { f32x2_t v = {lo, hi}; bf16x2_t b = __builtin_convertvector(v, bf16x2_t); return __builtin_bit_cast(unsigned, b); }
; __device__ __forceinline__ float sigmoidf_(float x) { return __builtin_amdgcn_rcpf(1.f + fexp2(-1.4426950408889634f * x)); }
; __device__ __forceinline__ void attn_epilogue(const f32x16& a0, const f32x16& a1, float scale, const bf16* zrow, bf16* orow, int hi) {
; #pragma unroll
;     for (int db = 0; db < 2; ++db)
; #pragma unroll
;         for (int p = 0; p < 2; ++p) {
;             const f32x16& o = db ? a1 : a0;
;             float x[4], y[4];
; #pragma unroll
;             for (int i = 0; i < 4; ++i) {
;                 auto rr = __builtin_amdgcn_permlane32_swap(__float_as_uint(o[8 * p + i]), __float_as_uint(o[8 * p + 4 + i]), false, false);
;                 x[i] = __uint_as_float(rr[0]); y[i] = __uint_as_float(rr[1]);
;             }
;             const int d = 32 * db + 8 * (2 * p + hi);
;             const v4u zz = *(const v4u*)(zrow + d);
;             f32x4 za, zb; unpack8(zz, za, zb);
;             float v[8];
; #pragma unroll
;             for (int i = 0; i < 4; ++i) { v[i] = x[i] * scale * za[i] * sigmoidf_(za[i]); v[4 + i] = y[i] * scale * zb[i] * sigmoidf_(zb[i]); }
;             *(v4u*)(orow + d) = (v4u){cvtpk(v[0], v[1]), cvtpk(v[2], v[3]), cvtpk(v[4], v[5]), cvtpk(v[6], v[7])};
;         }
; }
; __device__ __forceinline__ void moba_unit(const int wv, LAS unsigned char* lds, int b, int h, int qb, const bf16* Y, const float* kmean_l, bf16* OG) {
;     ...
;     __syncthreads();
	v_lshlrev_b32_e32 v34, 16, v96
	v_and_b32_e32 v35, 0xffff0000, v96
	v_mul_f32_e32 v28, 0xbfb8aa3b, v34
	v_exp_f32_e32 v28, v28
	v_pk_mul_f32 v[24:25], v[24:25], v[34:35]
	v_lshlrev_b32_e32 v34, 16, v98
	v_add_f32_e32 v28, 1.0, v28
	v_rcp_f32_e32 v36, v28
	v_mul_f32_e32 v28, 0xbfb8aa3b, v35
	v_exp_f32_e32 v28, v28
	v_and_b32_e32 v35, 0xffff0000, v98
	v_pk_mul_f32 v[22:23], v[22:23], v[34:35]
	v_add_f32_e32 v28, 1.0, v28
	v_rcp_f32_e32 v37, v28
	v_mul_f32_e32 v28, 0xbfb8aa3b, v34
	v_exp_f32_e32 v28, v28
	v_pk_mul_f32 v[24:25], v[24:25], v[36:37]
	v_add_f32_e32 v28, 1.0, v28
	v_rcp_f32_e32 v36, v28
	v_mul_f32_e32 v28, 0xbfb8aa3b, v35
	v_exp_f32_e32 v28, v28
	s_nop 0
	v_add_f32_e32 v28, 1.0, v28
	v_rcp_f32_e32 v37, v28
	s_nop 0
	v_pk_mul_f32 v[34:35], v[22:23], v[36:37]
	v_lshlrev_b32_e32 v22, 16, v97
	v_and_b32_e32 v23, 0xffff0000, v97
	v_mul_f32_e32 v28, 0xbfb8aa3b, v22
	v_pk_mul_f32 v[26:27], v[26:27], v[22:23]
	v_mul_f32_e32 v22, 0xbfb8aa3b, v23
	v_exp_f32_e32 v28, v28
	v_exp_f32_e32 v22, v22
	v_and_b32_e32 v23, 0xffff0000, v99
	v_add_f32_e32 v28, 1.0, v28
	v_add_f32_e32 v22, 1.0, v22
	v_rcp_f32_e32 v28, v28
	v_rcp_f32_e32 v29, v22
	v_lshlrev_b32_e32 v22, 16, v99
	v_pk_mul_f32 v[18:19], v[18:19], v[22:23]
	v_pk_mul_f32 v[26:27], v[26:27], v[28:29]
	v_mul_f32_e32 v28, 0xbfb8aa3b, v22
	v_mul_f32_e32 v22, 0xbfb8aa3b, v23
	v_exp_f32_e32 v28, v28
	v_exp_f32_e32 v22, v22
	v_cvt_pk_bf16_f32 v23, v26, v27
	v_add_f32_e32 v28, 1.0, v28
	v_add_f32_e32 v22, 1.0, v22
	v_rcp_f32_e32 v28, v28
	v_rcp_f32_e32 v29, v22
	v_cvt_pk_bf16_f32 v22, v24, v25
	v_cvt_pk_bf16_f32 v24, v34, v35
	v_pk_mul_f32 v[18:19], v[18:19], v[28:29]
	s_nop 0
	v_cvt_pk_bf16_f32 v25, v18, v19
	global_store_dwordx4 v[16:17], v[22:25], off offset:32
	v_mov_b32_e32 v18, v4
	v_mov_b32_e32 v19, v5
	v_mov_b32_e32 v22, v6
	v_mov_b32_e32 v23, v7
	v_permlane32_swap_b32_e32 v0, v18
	v_permlane32_swap_b32_e32 v1, v19
	v_pk_mul_f32 v[0:1], v[32:33], v[0:1] op_sel_hi:[0,1]
	v_permlane32_swap_b32_e32 v2, v22
	v_permlane32_swap_b32_e32 v3, v23
	v_pk_mul_f32 v[2:3], v[32:33], v[2:3] op_sel_hi:[0,1]
	v_pk_mul_f32 v[18:19], v[32:33], v[18:19] op_sel_hi:[0,1]
	v_pk_mul_f32 v[22:23], v[32:33], v[22:23] op_sel_hi:[0,1]
	s_waitcnt vmcnt(3)
	v_lshlrev_b32_e32 v24, 16, v100
	v_and_b32_e32 v25, 0xffff0000, v100
	v_mul_f32_e32 v4, 0xbfb8aa3b, v24
	v_exp_f32_e32 v4, v4
	v_pk_mul_f32 v[0:1], v[0:1], v[24:25]
	v_lshlrev_b32_e32 v24, 16, v102
	v_add_f32_e32 v4, 1.0, v4
	v_rcp_f32_e32 v26, v4
	v_mul_f32_e32 v4, 0xbfb8aa3b, v25
	v_exp_f32_e32 v4, v4
	v_and_b32_e32 v25, 0xffff0000, v102
	v_pk_mul_f32 v[18:19], v[18:19], v[24:25]
	v_add_f32_e32 v4, 1.0, v4
	v_rcp_f32_e32 v27, v4
	v_mul_f32_e32 v4, 0xbfb8aa3b, v24
	v_exp_f32_e32 v4, v4
	v_pk_mul_f32 v[0:1], v[0:1], v[26:27]
	s_nop 0
	v_cvt_pk_bf16_f32 v0, v0, v1
	v_add_f32_e32 v4, 1.0, v4
	v_rcp_f32_e32 v26, v4
	v_mul_f32_e32 v4, 0xbfb8aa3b, v25
	v_exp_f32_e32 v4, v4
	s_nop 0
	v_add_f32_e32 v4, 1.0, v4
	v_rcp_f32_e32 v27, v4
	v_lshlrev_b32_e32 v4, 16, v101
	v_and_b32_e32 v5, 0xffff0000, v101
	v_mul_f32_e32 v6, 0xbfb8aa3b, v4
	v_pk_mul_f32 v[2:3], v[2:3], v[4:5]
	v_mul_f32_e32 v4, 0xbfb8aa3b, v5
	v_exp_f32_e32 v4, v4
	v_exp_f32_e32 v6, v6
	v_and_b32_e32 v5, 0xffff0000, v103
	v_pk_mul_f32 v[18:19], v[18:19], v[26:27]
	v_add_f32_e32 v4, 1.0, v4
	v_add_f32_e32 v6, 1.0, v6
	v_rcp_f32_e32 v25, v4
	v_lshlrev_b32_e32 v4, 16, v103
	v_rcp_f32_e32 v24, v6
	v_mul_f32_e32 v6, 0xbfb8aa3b, v4
	v_pk_mul_f32 v[22:23], v[22:23], v[4:5]
	v_mul_f32_e32 v4, 0xbfb8aa3b, v5
	v_exp_f32_e32 v6, v6
	v_exp_f32_e32 v4, v4
	v_pk_mul_f32 v[2:3], v[2:3], v[24:25]
	v_add_f32_e32 v6, 1.0, v6
	v_add_f32_e32 v4, 1.0, v4
	v_rcp_f32_e32 v6, v6
	v_rcp_f32_e32 v7, v4
	v_cvt_pk_bf16_f32 v1, v2, v3
	v_cvt_pk_bf16_f32 v2, v18, v19
	v_pk_mul_f32 v[4:5], v[22:23], v[6:7]
	s_nop 0
	v_cvt_pk_bf16_f32 v3, v4, v5
	global_store_dwordx4 v[16:17], v[0:3], off offset:64
	v_mov_b32_e32 v6, v12
	v_mov_b32_e32 v7, v13
	v_mov_b32_e32 v4, v14
	v_permlane32_swap_b32_e32 v8, v6
	v_permlane32_swap_b32_e32 v9, v7
	v_pk_mul_f32 v[8:9], v[32:33], v[8:9] op_sel_hi:[0,1]
	v_mov_b32_e32 v5, v15
	v_permlane32_swap_b32_e32 v10, v4
	s_nop 0
	v_permlane32_swap_b32_e32 v11, v5
	v_pk_mul_f32 v[10:11], v[32:33], v[10:11] op_sel_hi:[0,1]
	v_pk_mul_f32 v[6:7], v[32:33], v[6:7] op_sel_hi:[0,1]
	v_pk_mul_f32 v[4:5], v[32:33], v[4:5] op_sel_hi:[0,1]
	s_waitcnt vmcnt(3)
	v_lshlrev_b32_e32 v12, 16, v104
	v_and_b32_e32 v13, 0xffff0000, v104
	v_mul_f32_e32 v0, 0xbfb8aa3b, v12
	v_exp_f32_e32 v0, v0
	v_pk_mul_f32 v[8:9], v[8:9], v[12:13]
	v_lshlrev_b32_e32 v12, 16, v106
	v_add_f32_e32 v0, 1.0, v0
	v_rcp_f32_e32 v14, v0
	v_mul_f32_e32 v0, 0xbfb8aa3b, v13
	v_exp_f32_e32 v0, v0
	v_and_b32_e32 v13, 0xffff0000, v106
	v_pk_mul_f32 v[6:7], v[6:7], v[12:13]
	v_add_f32_e32 v0, 1.0, v0
	v_rcp_f32_e32 v15, v0
	v_mul_f32_e32 v0, 0xbfb8aa3b, v12
	v_exp_f32_e32 v0, v0
	v_pk_mul_f32 v[8:9], v[8:9], v[14:15]
	v_add_f32_e32 v0, 1.0, v0
	v_rcp_f32_e32 v14, v0
	v_mul_f32_e32 v0, 0xbfb8aa3b, v13
	v_exp_f32_e32 v0, v0
	s_nop 0
	v_add_f32_e32 v0, 1.0, v0
	v_rcp_f32_e32 v15, v0
	v_lshlrev_b32_e32 v0, 16, v105
	v_and_b32_e32 v1, 0xffff0000, v105
	v_mul_f32_e32 v2, 0xbfb8aa3b, v0
	v_pk_mul_f32 v[10:11], v[10:11], v[0:1]
	v_mul_f32_e32 v0, 0xbfb8aa3b, v1
	v_exp_f32_e32 v0, v0
	v_exp_f32_e32 v2, v2
	v_and_b32_e32 v1, 0xffff0000, v107
	v_pk_mul_f32 v[6:7], v[6:7], v[14:15]
	v_add_f32_e32 v0, 1.0, v0
	v_add_f32_e32 v2, 1.0, v2
	v_rcp_f32_e32 v13, v0
	v_lshlrev_b32_e32 v0, 16, v107
	v_rcp_f32_e32 v12, v2
	v_mul_f32_e32 v2, 0xbfb8aa3b, v0
	v_pk_mul_f32 v[4:5], v[4:5], v[0:1]
	v_mul_f32_e32 v0, 0xbfb8aa3b, v1
	v_exp_f32_e32 v2, v2
	v_exp_f32_e32 v0, v0
	v_pk_mul_f32 v[10:11], v[10:11], v[12:13]
	v_add_f32_e32 v2, 1.0, v2
	v_add_f32_e32 v0, 1.0, v0
	v_rcp_f32_e32 v2, v2
	v_rcp_f32_e32 v3, v0
	v_cvt_pk_bf16_f32 v0, v8, v9
	v_cvt_pk_bf16_f32 v1, v10, v11
	v_pk_mul_f32 v[4:5], v[4:5], v[2:3]
	v_cvt_pk_bf16_f32 v2, v6, v7
	v_cvt_pk_bf16_f32 v3, v4, v5
	global_store_dwordx4 v[16:17], v[0:3], off offset:96
	s_barrier
	s_cbranch_scc1 .LBB0_1207
